# v92 + layer-0 pooling: pool GEMM units in panel order, context items co-located with their consumer's XCD, pool-elem(L0)->pool GEMM(L0) as a 3-panel hand-off (placement-checked)
# speedup vs baseline: 1.0121x; 1.0058x over previous
; __global__ void __launch_bounds__(NWAVES * 64, 2) fwd_kernel(Args args) {
;     ...
;                 const int nitems = (nrows / 64) * 4;
;                 f32x4 pv[10]; float rreg;
;     ...
;                 { const int it0_ = bx < nitems ? bx : 0; PL_PREFETCH(it0_); }
;                 for (int it = bx; it < nitems; it += G) {
.LBB0_1174:
	s_andn2_b64 vcc, exec, s[0:1]
	s_movk_i32 s30, 0x1fff
	s_movk_i32 s44, 0xff00
	s_cbranch_vccnz .LBB0_1372
	v_readlane_b32 s0, v255, 8
	v_readlane_b32 s1, v255, 9
	s_mov_b32 s2, s0
	s_cmp_lg_u32 s0, 0
	s_cselect_b64 s[0:1], -1, 0
	s_cmp_eq_u32 s2, 0
	s_movk_i32 s2, 0x420
	s_cselect_b32 s4, s2, 0x400
	s_waitcnt vmcnt(0)
	v_mov_b32_e32 v42, v215
	s_mov_b32 s23, s84
	s_mov_b32 s5, s82
	s_and_b32 s100, s84, 7
	s_lshl_b32 s100, s100, 3
	s_bfe_u32 s101, s84, 0x30003
	s_add_i32 s100, s100, s101
	s_lshl_b32 s100, s100, 4
	s_lshr_b32 s101, s84, 6
	s_add_i32 s23, s100, s101
	s_mov_b32 s5, 4
	s_bfe_u32 s101, s84, 0x10002
	s_lshl_b32 s101, s101, 4
	s_and_b32 s8, s84, 3
	s_add_i32 s101, s101, s8
	s_lshr_b32 s8, s84, 3
	s_lshl_b32 s8, s8, 2
	s_add_i32 s101, s101, s8
	s_addk_i32 s101, 0x400
	s_movk_i32 s8, 0x7fff
	s_cmp_lt_u32 s84, 32
	s_cselect_b32 s101, s101, s8
	s_add_i32 s8, s23, 16
	s_movk_i32 s100, 0x7fff
	s_cmpk_eq_u32 s4, 0x400
	s_cselect_b32 s101, s100, s101
	s_cselect_b32 s4, s8, s4
	s_mov_b32 s100, 0

; #define PHASE_END   } if (ph + 1 < hi) { if (lo < 0) grid.sync(); int tb_ = tid0; asm volatile("" : "+v"(tb_)); xcd_barrier(xbar, tb_); if ((PROBE_MASK >> 8) & 1) xcd_barrier(xbar, tb_); } } ++ph;
; __global__ void __launch_bounds__(NWAVES * 64, 2) fwd_kernel(Args args) {
;     ...
;                 }
;     ...
;                 if (layer == 0) {
;                 }
;             }
;             PHASE_END
.LBB0_1289:
	v_readlane_b32 s0, v254, 2
	s_add_i32 s4, s0, 1
	s_cmp_lt_i32 s4, s81
	s_cbranch_scc0 .LBB0_1372
	v_readlane_b32 s100, v255, 8
	s_cmp_eq_u32 s100, 0
	s_cbranch_scc0 .Lp0_orig
	v_readlane_b32 s100, v255, 57
	s_cmp_lg_u32 s100, 0
	s_cbranch_scc0 .Lp0_orig
	s_waitcnt vmcnt(0) lgkmcnt(0)
	s_barrier
	v_readlane_b32 s100, v255, 59
	s_add_i32 s100, s100, 1
	v_writelane_b32 v255, s100, 59
	v_cmp_eq_u32_e32 vcc, 0, v215
	s_and_saveexec_b64 s[0:1], vcc
	s_cbranch_execz .Lp0_w
	s_load_dwordx2 s[2:3], s[94:95], 0xb8
	s_lshl_b32 s100, s100, 2
	v_readlane_b32 s101, v255, 12
	s_and_b32 s6, s101, 63
	s_lshl_b32 s6, s6, 6
	s_cmp_lt_u32 s6, 0x800
	s_movk_i32 s7, 0x1400
	s_cselect_b32 s7, 0xc00, s7
	s_add_i32 s6, s6, s7
	v_mov_b32_e32 v0, s6
	v_mov_b32_e32 v1, 1
	s_and_b32 s6, s101, 7
	s_lshl_b32 s6, s6, 3
	s_bfe_u32 s7, s101, 0x30003
	s_add_i32 s8, s6, s7
	s_sub_i32 s6, s8, 1
	s_max_i32 s6, s6, 0
	s_lshr_b32 s7, s6, 3
	s_and_b32 s6, s6, 7
	s_lshl_b32 s6, s6, 3
	s_add_i32 s6, s6, s7
	s_lshl_b32 s6, s6, 6
	s_cmp_lt_u32 s6, 0x800
	s_movk_i32 s7, 0x1400
	s_cselect_b32 s7, 0xc00, s7
	s_add_i32 s6, s6, s7
	v_mov_b32_e32 v3, s6
	s_add_i32 s6, s8, 1
	s_min_i32 s6, s6, 63
	s_lshr_b32 s7, s6, 3
	s_and_b32 s6, s6, 7
	s_lshl_b32 s6, s6, 3
	s_add_i32 s6, s6, s7
	s_lshl_b32 s6, s6, 6
	s_cmp_lt_u32 s6, 0x800
	s_movk_i32 s7, 0x1400
	s_cselect_b32 s7, 0xc00, s7
	s_add_i32 s6, s6, s7
	v_mov_b32_e32 v4, s6
	s_bfe_u32 s6, s101, 0x10002
	s_lshl_b32 s6, s6, 5
	s_addk_i32 s6, 0x2c18
	v_mov_b32_e32 v5, s6
	s_lshr_b32 s6, s101, 2
	s_lshl_b32 s6, s6, 5
	s_addk_i32 s6, 0x2c18
	v_mov_b32_e32 v6, s6
	s_waitcnt lgkmcnt(0)
	s_add_u32 s2, s2, 0xe0000
	s_addc_u32 s3, s3, 0
	global_atomic_add v0, v1, s[2:3]
	s_cmp_lt_u32 s101, 32
	s_cbranch_scc0 .Lp0_nc
	global_atomic_add v5, v1, s[2:3]
.Lp0_nc:
	buffer_inv sc1
	s_mov_b32 s6, 0

.Lp0_d2:
	s_cmp_lt_u32 s101, 8
	s_cbranch_scc0 .Lp0_nx
	s_mov_b32 s6, 0
.Lp0_p3:
	global_load_dword v2, v6, s[2:3] sc1
	s_waitcnt vmcnt(0)
	v_cmp_le_u32_e32 vcc, 16, v2
	s_cbranch_vccnz .Lp0_d3
	s_sleep 1
	s_add_i32 s6, s6, 1
	s_cmp_lt_u32 s6, 0x100000
	s_cbranch_scc1 .Lp0_p3
.Lp0_d3:
.Lp0_nx:
	s_waitcnt vmcnt(0)

.Lp0_orig:
	v_readlane_b32 s100, v255, 8
	s_cmp_eq_u32 s100, 3
	s_cbranch_scc0 .Lp3_orig_2
	s_waitcnt vmcnt(0) lgkmcnt(0)
	s_barrier
	v_readlane_b32 s100, v255, 59
	s_add_i32 s100, s100, 1
	v_writelane_b32 v255, s100, 59
	v_cmp_eq_u32_e32 vcc, 0, v215
	s_and_saveexec_b64 s[0:1], vcc
	s_cbranch_execz .Lp3_w_2
	s_load_dwordx2 s[2:3], s[94:95], 0xb8
	s_lshl_b32 s100, s100, 2
	v_readlane_b32 s101, v255, 12
	s_and_b32 s6, s101, 63
	s_lshl_b32 s6, s6, 6
	s_cmp_lt_u32 s6, 0x800
	s_movk_i32 s7, 0x1400
	s_cselect_b32 s7, 0xc00, s7
	s_add_i32 s6, s6, s7
	v_mov_b32_e32 v0, s6
	v_mov_b32_e32 v1, 1
	s_and_b32 s6, s101, 7
	s_lshl_b32 s6, s6, 3
	s_bfe_u32 s7, s101, 0x30003
	s_add_i32 s101, s6, s7
	s_sub_i32 s6, s101, 1
	s_max_i32 s6, s6, 0
	s_lshr_b32 s7, s6, 3
	s_and_b32 s6, s6, 7
	s_lshl_b32 s6, s6, 3
	s_add_i32 s6, s6, s7
	s_lshl_b32 s6, s6, 6
	s_cmp_lt_u32 s6, 0x800
	s_movk_i32 s7, 0x1400
	s_cselect_b32 s7, 0xc00, s7
	s_add_i32 s6, s6, s7
	v_mov_b32_e32 v3, s6
	s_add_i32 s6, s101, 1
	s_min_i32 s6, s6, 63
	s_lshr_b32 s7, s6, 3
	s_and_b32 s6, s6, 7
	s_lshl_b32 s6, s6, 3
	s_add_i32 s6, s6, s7
	s_lshl_b32 s6, s6, 6
	s_cmp_lt_u32 s6, 0x800
	s_movk_i32 s7, 0x1400
	s_cselect_b32 s7, 0xc00, s7
	s_add_i32 s6, s6, s7
	v_mov_b32_e32 v4, s6
	s_waitcnt lgkmcnt(0)
	s_add_u32 s2, s2, 0xe0000
	s_addc_u32 s3, s3, 0
	global_atomic_add v0, v1, s[2:3]
	buffer_inv sc1
	s_mov_b32 s6, 0

;     __host__ __device__ bool next(int i, Unit& u) const {
;         const long L = (long)i * G + c; if (L >= nwg) return false;
;         int wgid = (int)L; { const int q = nwg / NXCD, r = nwg % NXCD, xcd = wgid % NXCD, off = wgid / NXCD; wgid = (xcd < r ? xcd * (q + 1) : r * (q + 1) + (xcd - r) * q) + off; }
;         const int nig = WGM * nN, gid = wgid / nig, fm = gid * WGM, gsz = (nM - fm) < WGM ? (nM - fm) : WGM;
;         u.pm = fm + ((wgid % nig) % gsz); u.pn = (wgid % nig) / gsz; return true;
.LBB0_1381:
	s_cmpk_lg_u32 s69, 0x42
	s_cbranch_scc1 .Lpg_map1
	s_and_b32 s44, s5, 7
	s_lshl_b32 s44, s44, 3
	s_bfe_u32 s18, s5, 0x30003
	s_add_i32 s44, s44, s18
	s_lshr_b32 s18, s5, 6

;     __host__ __device__ bool next(int i, Unit& u) const {
;         const long L = (long)i * G + c; if (L >= nwg) return false;
;         int wgid = (int)L; { const int q = nwg / NXCD, r = nwg % NXCD, xcd = wgid % NXCD, off = wgid / NXCD; wgid = (xcd < r ? xcd * (q + 1) : r * (q + 1) + (xcd - r) * q) + off; }
;         const int nig = WGM * nN, gid = wgid / nig, fm = gid * WGM, gsz = (nM - fm) < WGM ? (nM - fm) : WGM;
;         u.pm = fm + ((wgid % nig) % gsz); u.pn = (wgid % nig) / gsz; return true;
.LBB0_1387:
	s_add_i32 s23, s23, 1
	s_mul_i32 s8, s23, s21
	s_mul_hi_u32 s16, s23, s4
	s_add_i32 s16, s16, s8
	s_mul_i32 s8, s23, s4
	s_add_u32 s64, s8, s5
	s_addc_u32 s65, s16, s22
	s_waitcnt lgkmcnt(0)
	v_mov_b64_e32 v[0:1], s[14:15]
	v_cmp_ge_i64_e64 s[42:43], s[64:65], v[0:1]
	v_cmp_lt_i64_e64 s[40:41], s[64:65], v[0:1]
	s_and_b64 vcc, exec, s[42:43]
	s_cbranch_vccnz .LBB0_1408
	s_ashr_i32 s8, s64, 31
	s_lshr_b32 s8, s8, 29
	s_add_i32 s8, s64, s8
	s_ashr_i32 s16, s8, 3
	s_and_b32 s8, s8, -8
	s_sub_i32 s8, s64, s8
	s_lshr_b32 s19, s8, 31
	s_add_i32 s19, s86, s19
	s_mul_i32 s8, s19, s8
	s_add_i32 s8, s8, s16
	s_ashr_i32 s16, s8, 31
	s_lshr_b32 s16, s16, 27
	s_add_i32 s16, s8, s16
	s_ashr_i32 s19, s16, 5
	s_lshl_b32 s19, s19, 3
	s_sub_i32 s30, s69, s19
	s_min_i32 s30, s30, 8
	s_abs_i32 s45, s30
	v_cvt_f32_u32_e32 v0, s45
	s_sub_i32 s53, 0, s45
	s_andn2_b32 s16, s16, 31
	s_sub_i32 s8, s8, s16
	v_rcp_iflag_f32_e32 v0, v0
	s_abs_i32 s16, s8
	s_xor_b32 s52, s8, s30
	s_ashr_i32 s52, s52, 31
	v_mul_f32_e32 v0, 0x4f7ffffe, v0
	v_cvt_u32_f32_e32 v0, v0
	s_nop 0
	v_readfirstlane_b32 s54, v0
	s_mul_i32 s53, s53, s54
	s_mul_hi_u32 s53, s54, s53
	s_add_i32 s54, s54, s53
	s_mul_hi_u32 s53, s16, s54
	s_mul_i32 s54, s53, s45
	s_sub_i32 s16, s16, s54
	s_add_i32 s55, s53, 1
	s_sub_i32 s54, s16, s45
	s_cmp_ge_u32 s16, s45
	s_cselect_b32 s53, s55, s53
	s_cselect_b32 s16, s54, s16
	s_add_i32 s54, s53, 1
	s_cmp_ge_u32 s16, s45
	s_cselect_b32 s16, s54, s53
	s_xor_b32 s16, s16, s52
	s_sub_i32 s60, s16, s52
	s_mul_i32 s16, s60, s30
	s_sub_i32 s8, s8, s16
	s_add_i32 s62, s8, s19
	s_cmpk_lg_u32 s69, 0x42
	s_cbranch_scc1 .Lpg_map2
	s_lshr_b32 s62, s5, 2
	s_add_i32 s62, s62, 64
	s_and_b32 s60, s5, 3
.Lpg_map2:
	s_andn2_b64 vcc, exec, s[42:43]
	s_mov_b64 s[42:43], -1
	s_cbranch_vccz .LBB0_1409
